# MLA V1 LDS streaming + removed the functionally unneeded cooperative-groups grid.sync at kernel start
# speedup vs baseline: 1.0260x; 1.0084x over previous
_Z14fwd_megakernel6Params:
	s_mov_b32 s94, s2
	s_add_u32 s2, s0, 0xf8
	s_addc_u32 s3, s1, 0
	s_load_dwordx2 s[36:37], s[0:1], 0xf8
	v_writelane_b32 v255, s2, 0
	v_and_b32_e32 v190, 0x3ff, v0
	v_mov_b32_e32 v1, v190
	v_writelane_b32 v255, s3, 1
	v_writelane_b32 v255, s0, 2
	s_load_dword s33, s[0:1], 0x100
	s_nop 0
	v_writelane_b32 v255, s1, 3
	v_cmp_gt_i32_e32 vcc, 4, v1
	s_and_saveexec_b64 s[0:1], vcc
	v_lshl_add_u32 v1, v1, 2, 0
	v_add_u32_e32 v1, 0x24400, v1
	v_mov_b32_e32 v2, 0
	ds_write_b32 v1, v2
	s_or_b64 exec, exec, s[0:1]
	v_readlane_b32 s0, v255, 2
	v_readlane_b32 s1, v255, 3
	s_waitcnt lgkmcnt(0)
	s_barrier
	s_load_dwordx2 s[0:1], s[0:1], 0xf0
	v_mov_b32_e32 v1, v190
	s_getreg_b32 s4, hwreg(HW_REG_XCC_ID, 0, 4)
	s_waitcnt lgkmcnt(0)
	v_writelane_b32 v255, s0, 4
	v_cmp_eq_u32_e32 vcc, 0, v1
	s_nop 0
	v_writelane_b32 v255, s1, 5
	s_and_saveexec_b64 s[0:1], vcc
	s_cbranch_execz .LBB0_5
	s_mov_b64 s[2:3], exec
	v_mbcnt_lo_u32_b32 v1, s2, 0
	v_mbcnt_hi_u32_b32 v1, s3, v1
	v_cmp_eq_u32_e32 vcc, 0, v1
	s_and_b64 s[6:7], exec, vcc
	s_mov_b64 exec, s[6:7]
	s_cbranch_execz .LBB0_5
	s_lshl_b32 s4, s4, 8
	s_and_b32 s4, s4, 0xf00
	v_readlane_b32 s6, v255, 4
	v_readlane_b32 s7, v255, 5
	s_add_u32 s4, s6, s4
	s_addc_u32 s5, s7, 0
	s_bcnt1_i32_b64 s2, s[2:3]
	v_mov_b32_e32 v1, 0xf37a000
	v_mov_b32_e32 v2, s2
	global_atomic_add v1, v2, s[4:5] offset:1024
.LBB0_5:
	s_or_b64 exec, exec, s[0:1]
	v_readlane_b32 s0, v255, 2
	v_readlane_b32 s1, v255, 3
	v_mov_b32_e32 v8, v190
	s_movk_i32 s2, 0xc00
	s_barrier
	s_nop 0
	v_cmp_gt_i32_e64 s[2:3], s2, v8
	s_and_saveexec_b64 s[4:5], s[2:3]
	s_cbranch_execz .LBB0_22
	v_ashrrev_i32_e32 v9, 31, v8
	v_lshlrev_b64 v[0:1], 2, v[8:9]
	v_lshl_add_u32 v6, v8, 2, 0
	s_mov_b64 s[6:7], 0
	s_movk_i32 s12, 0x7ff
	v_mov_b32_e32 v3, 0
	s_mov_b64 s[8:9], 0x800
	s_movk_i32 s13, 0x9ff
	v_mov_b32_e32 v7, v8
	s_branch .LBB0_18
